# in-proj GEMM: per-128B-line LDS-DMA landing sentinels (conflict-free), conv unit rewrite, phase0 load de-serialisation
# speedup vs baseline: 1.0554x; 1.0195x over previous
.LBB0_270:
	s_and_b64 s[0:1], s[20:21], exec
	s_mov_b32 s10, 208
	s_mov_b32 s11, 20648882
	s_mov_b32 s12, 6656
	s_mov_b32 s1, 2496
	s_cmov_b32 s10, 168
	s_cmov_b32 s11, 25565282
	s_cmov_b32 s12, 5376
	s_cmov_b32 s1, 2016
	v_readlane_b32 s28, v252, 0
	v_readlane_b32 s6, v252, 1
	s_lshr_b32 s6, s6, 3
	s_and_b32 s0, s28, 7
	s_mul_i32 s0, s0, s6
	s_lshr_b32 s28, s28, 3
	s_add_u32 s0, s0, s28
	s_lshl_b32 s6, s6, 3
	s_cmp_ge_u32 s0, s1
	s_cbranch_scc1 .Lgin_done
	v_and_b32_e32 v128, 31, v193
	v_lshlrev_b32_e32 v129, 7, v128
	v_bfe_u32 v130, v193, 1, 3
	v_bfe_u32 v131, v193, 5, 1
	v_xor_b32_e32 v130, v130, v131
	v_bfe_u32 v131, v193, 7, 1
	v_lshl_add_u32 v131, v131, 14, v129
	v_bfe_u32 v132, v193, 6, 1
	v_lshl_add_u32 v132, v132, 13, v129
	v_lshl_add_u32 v144, v130, 4, v131
	v_lshl_add_u32 v211, v130, 4, v132
	v_xor_b32_e32 v128, 2, v130
	v_lshl_add_u32 v146, v128, 4, v131
	v_lshl_add_u32 v248, v128, 4, v132
	v_xor_b32_e32 v128, 4, v130
	v_lshl_add_u32 v147, v128, 4, v131
	v_lshl_add_u32 v249, v128, 4, v132
	v_xor_b32_e32 v128, 6, v130
	v_lshl_add_u32 v210, v128, 4, v131
	v_lshl_add_u32 v250, v128, 4, v132
	v_and_b32_e32 v128, 7, v193
	v_bfe_u32 v129, v193, 4, 3
	v_xor_b32_e32 v128, v128, v129
	v_lshrrev_b32_e32 v129, 3, v193
	v_lshlrev_b32_e32 v129, 11, v129
	v_lshl_add_u32 v251, v128, 4, v129
	v_lshrrev_b32_e32 v128, 6, v193
	v_lshlrev_b32_e32 v128, 10, v128
	s_nop 0
	v_readfirstlane_b32 s22, v128
	v_bfe_u32 v129, v193, 3, 3
	v_lshl_add_u32 v128, v129, 12, v128
	v_and_b32_e32 v129, 7, v193
	v_lshl_add_u32 v128, v129, 7, v128
	v_lshl_add_u32 v128, v129, 2, v128
	v_lshrrev_b32_e32 v129, 6, v193
	v_lshl_add_u32 v145, v129, 5, v128
.Lgin_tile:
	s_mul_hi_u32 s28, s0, s11
	s_mul_i32 vcc_lo, s28, s10
	s_sub_u32 vcc_lo, s0, vcc_lo
	s_lshr_b32 vcc_hi, vcc_lo, 3
	s_and_b32 vcc_lo, vcc_lo, 7
	s_lshl_b32 s28, s28, 3
	s_add_u32 s28, s28, vcc_lo
	s_lshl_b32 s20, s28, 19
	s_add_u32 s20, s20, 29876224
	s_add_u32 s20, s94, s20
	s_addc_u32 s21, s95, 0
	s_lshl_b32 s24, vcc_hi, 18
	s_add_u32 s24, s94, s24
	s_addc_u32 s25, s95, 0
	s_mul_i32 s26, s28, s12
	s_lshl_b32 s26, s26, 8
	s_lshl_b32 vcc_hi, vcc_hi, 8
	s_add_u32 s26, s26, vcc_hi
	s_add_u32 s26, s34, s26
	s_addc_u32 s27, s35, 0
	ds_write_b32 v145, v145
	s_mov_b32 exec_hi, 0
	ds_write_b32 v145, v145 offset:32768
	s_mov_b32 exec_hi, -1
	s_waitcnt lgkmcnt(0)
	s_mov_b32 m0, s22
	s_nop 0
	global_load_lds_dwordx4 v251, s[20:21]
	s_add_u32 m0, m0, 0x1000
	s_add_u32 s20, s20, 0x10000
	s_addc_u32 s21, s21, 0
	global_load_lds_dwordx4 v251, s[20:21]
	s_add_u32 m0, m0, 0x1000
	s_add_u32 s20, s20, 0x10000
	s_addc_u32 s21, s21, 0
	global_load_lds_dwordx4 v251, s[20:21]
	s_add_u32 m0, m0, 0x1000
	s_add_u32 s20, s20, 0x10000
	s_addc_u32 s21, s21, 0
	global_load_lds_dwordx4 v251, s[20:21]
	s_add_u32 m0, m0, 0x1000
	s_add_u32 s20, s20, 0x10000
	s_addc_u32 s21, s21, 0
	global_load_lds_dwordx4 v251, s[20:21]
	s_add_u32 m0, m0, 0x1000
	s_add_u32 s20, s20, 0x10000
	s_addc_u32 s21, s21, 0
	global_load_lds_dwordx4 v251, s[20:21]
	s_add_u32 m0, m0, 0x1000
	s_add_u32 s20, s20, 0x10000
	s_addc_u32 s21, s21, 0
	global_load_lds_dwordx4 v251, s[20:21]
	s_add_u32 m0, m0, 0x1000
	s_add_u32 s20, s20, 0x10000
	s_addc_u32 s21, s21, 0
	global_load_lds_dwordx4 v251, s[20:21]
	s_add_u32 m0, m0, 0x1000
	s_sub_u32 s20, s20, 458624
	s_subb_u32 s21, s21, 0
	global_load_lds_dwordx4 v251, s[24:25]
	s_add_u32 m0, m0, 0x1000
	s_add_u32 s24, s24, 0x10000
	s_addc_u32 s25, s25, 0
	global_load_lds_dwordx4 v251, s[24:25]
	s_add_u32 m0, m0, 0x1000
	s_add_u32 s24, s24, 0x10000
	s_addc_u32 s25, s25, 0
	global_load_lds_dwordx4 v251, s[24:25]
	s_add_u32 m0, m0, 0x1000
	s_add_u32 s24, s24, 0x10000
	s_addc_u32 s25, s25, 0
	global_load_lds_dwordx4 v251, s[24:25]
	s_sub_u32 s24, s24, 196480
	s_subb_u32 s25, s25, 0
	v_mov_b32_e32 v0, 0
	v_mov_b32_e32 v1, 0
	v_mov_b32_e32 v2, 0
	v_mov_b32_e32 v3, 0
	v_mov_b32_e32 v4, 0
	v_mov_b32_e32 v5, 0
	v_mov_b32_e32 v6, 0
	v_mov_b32_e32 v7, 0
	v_mov_b32_e32 v8, 0
	v_mov_b32_e32 v9, 0
	v_mov_b32_e32 v10, 0
	v_mov_b32_e32 v11, 0
	v_mov_b32_e32 v12, 0
	v_mov_b32_e32 v13, 0
	v_mov_b32_e32 v14, 0
	v_mov_b32_e32 v15, 0
	v_mov_b32_e32 v16, 0
	v_mov_b32_e32 v17, 0
	v_mov_b32_e32 v18, 0
	v_mov_b32_e32 v19, 0
	v_mov_b32_e32 v20, 0
	v_mov_b32_e32 v21, 0
	v_mov_b32_e32 v22, 0
	v_mov_b32_e32 v23, 0
	v_mov_b32_e32 v24, 0
	v_mov_b32_e32 v25, 0
	v_mov_b32_e32 v26, 0
	v_mov_b32_e32 v27, 0
	v_mov_b32_e32 v28, 0
	v_mov_b32_e32 v29, 0
	v_mov_b32_e32 v30, 0
	v_mov_b32_e32 v31, 0
	v_mov_b32_e32 v32, 0
	v_mov_b32_e32 v33, 0
	v_mov_b32_e32 v34, 0
	v_mov_b32_e32 v35, 0
	v_mov_b32_e32 v36, 0
	v_mov_b32_e32 v37, 0
	v_mov_b32_e32 v38, 0
	v_mov_b32_e32 v39, 0
	v_mov_b32_e32 v40, 0
	v_mov_b32_e32 v41, 0
	v_mov_b32_e32 v42, 0
	v_mov_b32_e32 v43, 0
	v_mov_b32_e32 v44, 0
	v_mov_b32_e32 v45, 0
	v_mov_b32_e32 v46, 0
	v_mov_b32_e32 v47, 0
	v_mov_b32_e32 v48, 0
	v_mov_b32_e32 v49, 0
	v_mov_b32_e32 v50, 0
	v_mov_b32_e32 v51, 0
	v_mov_b32_e32 v52, 0
	v_mov_b32_e32 v53, 0
	v_mov_b32_e32 v54, 0
	v_mov_b32_e32 v55, 0
	v_mov_b32_e32 v56, 0
	v_mov_b32_e32 v57, 0
	v_mov_b32_e32 v58, 0
	v_mov_b32_e32 v59, 0
	v_mov_b32_e32 v60, 0
	v_mov_b32_e32 v61, 0
	v_mov_b32_e32 v62, 0
	v_mov_b32_e32 v63, 0
	v_mov_b32_e32 v64, 0
	v_mov_b32_e32 v65, 0
	v_mov_b32_e32 v66, 0
	v_mov_b32_e32 v67, 0
	v_mov_b32_e32 v68, 0
	v_mov_b32_e32 v69, 0
	v_mov_b32_e32 v70, 0
	v_mov_b32_e32 v71, 0
	v_mov_b32_e32 v72, 0
	v_mov_b32_e32 v73, 0
	v_mov_b32_e32 v74, 0
	v_mov_b32_e32 v75, 0
	v_mov_b32_e32 v76, 0
	v_mov_b32_e32 v77, 0
	v_mov_b32_e32 v78, 0
	v_mov_b32_e32 v79, 0
	v_mov_b32_e32 v80, 0
	v_mov_b32_e32 v81, 0
	v_mov_b32_e32 v82, 0
	v_mov_b32_e32 v83, 0
	v_mov_b32_e32 v84, 0
	v_mov_b32_e32 v85, 0
	v_mov_b32_e32 v86, 0
	v_mov_b32_e32 v87, 0
	v_mov_b32_e32 v88, 0
	v_mov_b32_e32 v89, 0
	v_mov_b32_e32 v90, 0
	v_mov_b32_e32 v91, 0
	v_mov_b32_e32 v92, 0
	v_mov_b32_e32 v93, 0
	v_mov_b32_e32 v94, 0
	v_mov_b32_e32 v95, 0
	v_mov_b32_e32 v96, 0
	v_mov_b32_e32 v97, 0
	v_mov_b32_e32 v98, 0
	v_mov_b32_e32 v99, 0
	v_mov_b32_e32 v100, 0
	v_mov_b32_e32 v101, 0
	v_mov_b32_e32 v102, 0
	v_mov_b32_e32 v103, 0
	v_mov_b32_e32 v104, 0
	v_mov_b32_e32 v105, 0
	v_mov_b32_e32 v106, 0
	v_mov_b32_e32 v107, 0
	v_mov_b32_e32 v108, 0
	v_mov_b32_e32 v109, 0
	v_mov_b32_e32 v110, 0
	v_mov_b32_e32 v111, 0
	v_mov_b32_e32 v112, 0
	v_mov_b32_e32 v113, 0
	v_mov_b32_e32 v114, 0
	v_mov_b32_e32 v115, 0
	v_mov_b32_e32 v116, 0
	v_mov_b32_e32 v117, 0
	v_mov_b32_e32 v118, 0
	v_mov_b32_e32 v119, 0
	v_mov_b32_e32 v120, 0
	v_mov_b32_e32 v121, 0
	v_mov_b32_e32 v122, 0
	v_mov_b32_e32 v123, 0
	v_mov_b32_e32 v124, 0
	v_mov_b32_e32 v125, 0
	v_mov_b32_e32 v126, 0
	v_mov_b32_e32 v127, 0
	s_mov_b32 s16, 16
.Lgin_k:
	s_waitcnt vmcnt(0)
	s_barrier
	v_and_b32_e32 v128, 63, v193
	v_and_b32_e32 v135, 31, v193
	v_lshlrev_b32_e32 v128, 7, v128
	v_lshl_add_u32 v128, v135, 2, v128
	v_add_u32_e32 v135, 0x2000, v128
	v_add_u32_e32 v136, 0x4000, v128
	v_add_u32_e32 v137, 0x6000, v128
	s_mov_b32 s28, 64
.Lgin_poll:
	ds_read_b32 v129, v128
	ds_read_b32 v130, v128 offset:8192
	ds_read_b32 v131, v128 offset:16384
	ds_read_b32 v132, v128 offset:24576
	ds_read_b32 v133, v128 offset:32768
	ds_read_b32 v134, v128 offset:40960
	s_waitcnt lgkmcnt(5)
	v_xor_b32_e32 v129, v129, v128
	s_waitcnt lgkmcnt(4)
	v_xor_b32_e32 v130, v130, v135
	s_waitcnt lgkmcnt(3)
	v_xor_b32_e32 v131, v131, v136
	s_waitcnt lgkmcnt(2)
	v_xor_b32_e32 v132, v132, v137
	s_waitcnt lgkmcnt(1)
	v_xor_b32_e32 v133, v133, v128
	s_waitcnt lgkmcnt(0)
	v_xor_b32_e32 v134, v134, v135
	v_min_u32_e32 v129, v129, v130
	v_min_u32_e32 v131, v131, v132
	v_min_u32_e32 v133, v133, v134
	v_min3_u32 v129, v129, v131, v133
	v_cmp_eq_u32_e32 vcc, 0, v129
	s_cbranch_vccz .Lgin_pollok
	s_sub_u32 s28, s28, 1
	s_cmp_lg_u32 s28, 0
	s_cbranch_scc1 .Lgin_poll
.Lgin_pollok:
	ds_read_b128 v[128:131], v144 offset:0
	ds_read_b128 v[148:151], v144 offset:4096
	ds_read_b128 v[164:167], v144 offset:8192
	ds_read_b128 v[180:183], v144 offset:12288
	ds_read_b128 v[132:135], v146 offset:0
	ds_read_b128 v[152:155], v146 offset:4096
	ds_read_b128 v[168:171], v146 offset:8192
	ds_read_b128 v[184:187], v146 offset:12288
	ds_read_b128 v[136:139], v147 offset:0
	ds_read_b128 v[156:159], v147 offset:4096
	ds_read_b128 v[172:175], v147 offset:8192
	ds_read_b128 v[188:191], v147 offset:12288
	ds_read_b128 v[140:143], v210 offset:0
	ds_read_b128 v[160:163], v210 offset:4096
	ds_read_b128 v[176:179], v210 offset:8192
	ds_read_b128 v[212:215], v210 offset:12288
	ds_read_b128 v[216:219], v211 offset:32768
	ds_read_b128 v[232:235], v211 offset:36864
	ds_read_b128 v[220:223], v248 offset:32768
	ds_read_b128 v[236:239], v248 offset:36864
	ds_read_b128 v[224:227], v249 offset:32768
	ds_read_b128 v[240:243], v249 offset:36864
	ds_read_b128 v[228:231], v250 offset:32768
	ds_read_b128 v[244:247], v250 offset:36864
	s_waitcnt lgkmcnt(0)
	s_barrier
	s_cmp_eq_u32 s16, 1
	s_cbranch_scc1 .Lgin_nodma
	ds_write_b32 v145, v145
	s_mov_b32 exec_hi, 0
	ds_write_b32 v145, v145 offset:32768
	s_mov_b32 exec_hi, -1
	s_waitcnt lgkmcnt(0)
	s_mov_b32 m0, s22
	s_nop 0
	global_load_lds_dwordx4 v251, s[20:21]
	s_add_u32 m0, m0, 0x1000
	s_add_u32 s20, s20, 0x10000
	s_addc_u32 s21, s21, 0
	global_load_lds_dwordx4 v251, s[20:21]
	s_add_u32 m0, m0, 0x1000
	s_add_u32 s20, s20, 0x10000
	s_addc_u32 s21, s21, 0
	global_load_lds_dwordx4 v251, s[20:21]
	s_add_u32 m0, m0, 0x1000
	s_add_u32 s20, s20, 0x10000
	s_addc_u32 s21, s21, 0
	global_load_lds_dwordx4 v251, s[20:21]
	s_add_u32 m0, m0, 0x1000
	s_add_u32 s20, s20, 0x10000
	s_addc_u32 s21, s21, 0
	global_load_lds_dwordx4 v251, s[20:21]
	s_add_u32 m0, m0, 0x1000
	s_add_u32 s20, s20, 0x10000
	s_addc_u32 s21, s21, 0
	global_load_lds_dwordx4 v251, s[20:21]
	s_add_u32 m0, m0, 0x1000
	s_add_u32 s20, s20, 0x10000
	s_addc_u32 s21, s21, 0
	global_load_lds_dwordx4 v251, s[20:21]
	s_add_u32 m0, m0, 0x1000
	s_add_u32 s20, s20, 0x10000
	s_addc_u32 s21, s21, 0
	global_load_lds_dwordx4 v251, s[20:21]
	s_add_u32 m0, m0, 0x1000
	s_sub_u32 s20, s20, 458624
	s_subb_u32 s21, s21, 0
	global_load_lds_dwordx4 v251, s[24:25]
	s_add_u32 m0, m0, 0x1000
	s_add_u32 s24, s24, 0x10000
	s_addc_u32 s25, s25, 0
	global_load_lds_dwordx4 v251, s[24:25]
	s_add_u32 m0, m0, 0x1000
	s_add_u32 s24, s24, 0x10000
	s_addc_u32 s25, s25, 0
	global_load_lds_dwordx4 v251, s[24:25]
	s_add_u32 m0, m0, 0x1000
	s_add_u32 s24, s24, 0x10000
	s_addc_u32 s25, s25, 0
	global_load_lds_dwordx4 v251, s[24:25]
	s_sub_u32 s24, s24, 196480
	s_subb_u32 s25, s25, 0

.LBB0_337:
	s_movk_i32 s0, 0x3ff
	v_cmp_lt_i32_e32 vcc, s0, v10
	s_and_saveexec_b64 s[0:1], vcc
	s_xor_b64 s[20:21], exec, s[0:1]
	s_cbranch_execz .LBB0_396
	s_movk_i32 s0, 0x5ff
	v_cmp_lt_u32_e32 vcc, s0, v10
	s_and_saveexec_b64 s[0:1], vcc
	s_xor_b64 s[26:27], exec, s[0:1]
	s_cbranch_execz .LBB0_376
	v_readfirstlane_b32 s0, v10
	v_lshrrev_b32_e32 v208, 6, v193
	v_and_b32_e32 v209, 63, v193
	v_readfirstlane_b32 s1, v208
	s_sub_u32 s0, s0, 0x600
	s_lshl_b32 s0, s0, 4
	s_movk_i32 s6, 0xfff
	s_cmp_lt_u32 s0, 0x2000
	s_cmov_b32 s6, 0xff
	s_and_b32 vcc_lo, s0, s6
	s_cmp_lg_u32 vcc_lo, 0
	s_cselect_b32 s98, 1.0, 0
	s_add_u32 vcc_lo, s0, 16
	s_and_b32 vcc_lo, vcc_lo, s6
	s_cmp_lg_u32 vcc_lo, 0
	s_cselect_b32 s99, 1.0, 0
	s_cmp_eq_u32 s1, 0
	s_cselect_b32 s98, s98, 1.0
	s_cmp_eq_u32 s1, 3
	s_cselect_b32 s99, s99, 1.0
	s_lshl_b32 s1, s1, 2
	s_add_u32 s0, s0, s1
	v_lshlrev_b32_e32 v0, 4, v209
	v_add_u32_e32 v4, 0x400, v0
	v_add_u32_e32 v5, 0x1400, v0
	v_add_u32_e32 v0, 0xa00, v0
	v_lshlrev_b32_e32 v1, 5, v209
	v_add_u32_e32 v2, 0x1000, v1
	s_lshl_b32 s6, s55, 2
	v_add_u32_e32 v3, s6, v1
	global_load_dwordx4 v[96:99], v1, s[40:41]
	global_load_dwordx4 v[100:103], v1, s[40:41] offset:16
	global_load_dwordx4 v[104:107], v1, s[40:41] offset:2048
	global_load_dwordx4 v[108:111], v1, s[40:41] offset:2064
	global_load_dwordx4 v[112:115], v2, s[40:41]
	global_load_dwordx4 v[116:119], v2, s[40:41] offset:16
	global_load_dwordx4 v[120:123], v3, s[90:91]
	global_load_dwordx4 v[124:127], v3, s[90:91] offset:16
	s_max_u32 s6, s0, 1
	s_sub_u32 s6, s6, 1
	s_mul_i32 s6, s6, 0x1a00
	s_add_u32 s28, s34, s6
	s_addc_u32 s29, s35, 0
	global_load_dwordx4 v[16:19], v0, s[28:29]
	global_load_dwordx4 v[40:43], v0, s[28:29] offset:2048
	s_lshl_b32 s6, s0, 11
	s_add_u32 s6, s6, 29876224
	s_add_u32 s100, s94, s6
	s_addc_u32 s101, s95, 0
	s_mul_i32 s6, s0, 0x1a00
	s_add_u32 s28, s34, s6
	s_addc_u32 s29, s35, 0
	global_load_dwordx4 v[20:23], v0, s[28:29]
	global_load_dwordx4 v[64:67], v0, s[28:29] offset:1024
	global_load_dwordx4 v[44:47], v0, s[28:29] offset:2048
	global_load_dwordx4 v[80:83], v0, s[28:29] offset:3072
	s_nop 0
	s_add_u32 s28, s28, 0x1a00
	s_addc_u32 s29, s29, 0
	global_load_dwordx4 v[24:27], v0, s[28:29]
	global_load_dwordx4 v[68:71], v0, s[28:29] offset:1024
	global_load_dwordx4 v[48:51], v0, s[28:29] offset:2048
	global_load_dwordx4 v[84:87], v0, s[28:29] offset:3072
	s_nop 0
	s_add_u32 s28, s28, 0x1a00
	s_addc_u32 s29, s29, 0
	global_load_dwordx4 v[28:31], v0, s[28:29]
	global_load_dwordx4 v[72:75], v0, s[28:29] offset:1024
	global_load_dwordx4 v[52:55], v0, s[28:29] offset:2048
	global_load_dwordx4 v[88:91], v0, s[28:29] offset:3072
	s_nop 0
	s_add_u32 s28, s28, 0x1a00
	s_addc_u32 s29, s29, 0
	global_load_dwordx4 v[32:35], v0, s[28:29]
	global_load_dwordx4 v[76:79], v0, s[28:29] offset:1024
	global_load_dwordx4 v[56:59], v0, s[28:29] offset:2048
	global_load_dwordx4 v[92:95], v0, s[28:29] offset:3072
	s_add_u32 s6, s0, 4
	s_min_u32 s6, s6, 0x5fff
	s_mul_i32 s6, s6, 0x1a00
	s_add_u32 s28, s34, s6
	s_addc_u32 s29, s35, 0
	global_load_dwordx4 v[36:39], v0, s[28:29]
	global_load_dwordx4 v[60:63], v0, s[28:29] offset:2048
	s_waitcnt vmcnt(0)
	v_lshlrev_b32_e32 v208, 16, v16
	v_and_b32_e32 v209, 0xffff0000, v16
	v_lshlrev_b32_e32 v210, 16, v17
	v_and_b32_e32 v211, 0xffff0000, v17
	v_lshlrev_b32_e32 v212, 16, v18
	v_and_b32_e32 v213, 0xffff0000, v18
	v_lshlrev_b32_e32 v214, 16, v19
	v_and_b32_e32 v215, 0xffff0000, v19
	v_lshlrev_b32_e32 v216, 16, v40
	v_and_b32_e32 v217, 0xffff0000, v40
	v_lshlrev_b32_e32 v218, 16, v41
	v_and_b32_e32 v219, 0xffff0000, v41
	v_lshlrev_b32_e32 v220, 16, v42
	v_and_b32_e32 v221, 0xffff0000, v42
	v_lshlrev_b32_e32 v222, 16, v43
	v_and_b32_e32 v223, 0xffff0000, v43
	v_pk_mul_f32 v[128:129], v[208:209], v[216:217]
	v_pk_mul_f32 v[130:131], v[210:211], v[218:219]
	v_pk_mul_f32 v[132:133], v[212:213], v[220:221]
	v_pk_mul_f32 v[134:135], v[214:215], v[222:223]
	v_lshlrev_b32_e32 v208, 16, v20
	v_and_b32_e32 v209, 0xffff0000, v20
	v_lshlrev_b32_e32 v210, 16, v21
	v_and_b32_e32 v211, 0xffff0000, v21
	v_lshlrev_b32_e32 v212, 16, v22
	v_and_b32_e32 v213, 0xffff0000, v22
	v_lshlrev_b32_e32 v214, 16, v23
	v_and_b32_e32 v215, 0xffff0000, v23
	v_lshlrev_b32_e32 v216, 16, v44
	v_and_b32_e32 v217, 0xffff0000, v44
	v_lshlrev_b32_e32 v218, 16, v45
	v_and_b32_e32 v219, 0xffff0000, v45
	v_lshlrev_b32_e32 v220, 16, v46
	v_and_b32_e32 v221, 0xffff0000, v46
	v_lshlrev_b32_e32 v222, 16, v47
	v_and_b32_e32 v223, 0xffff0000, v47
	v_pk_mul_f32 v[136:137], v[208:209], v[216:217]
	v_pk_mul_f32 v[138:139], v[210:211], v[218:219]
	v_pk_mul_f32 v[140:141], v[212:213], v[220:221]
	v_pk_mul_f32 v[142:143], v[214:215], v[222:223]
	v_lshlrev_b32_e32 v208, 16, v24
	v_and_b32_e32 v209, 0xffff0000, v24
	v_lshlrev_b32_e32 v210, 16, v25
	v_and_b32_e32 v211, 0xffff0000, v25
	v_lshlrev_b32_e32 v212, 16, v26
	v_and_b32_e32 v213, 0xffff0000, v26
	v_lshlrev_b32_e32 v214, 16, v27
	v_and_b32_e32 v215, 0xffff0000, v27
	v_lshlrev_b32_e32 v216, 16, v48
	v_and_b32_e32 v217, 0xffff0000, v48
	v_lshlrev_b32_e32 v218, 16, v49
	v_and_b32_e32 v219, 0xffff0000, v49
	v_lshlrev_b32_e32 v220, 16, v50
	v_and_b32_e32 v221, 0xffff0000, v50
	v_lshlrev_b32_e32 v222, 16, v51
	v_and_b32_e32 v223, 0xffff0000, v51
	v_pk_mul_f32 v[146:147], v[208:209], v[216:217]
	v_pk_mul_f32 v[148:149], v[210:211], v[218:219]
	v_pk_mul_f32 v[150:151], v[212:213], v[220:221]
	v_pk_mul_f32 v[152:153], v[214:215], v[222:223]
	v_lshlrev_b32_e32 v208, 16, v28
	v_and_b32_e32 v209, 0xffff0000, v28
	v_lshlrev_b32_e32 v210, 16, v29
	v_and_b32_e32 v211, 0xffff0000, v29
	v_lshlrev_b32_e32 v212, 16, v30
	v_and_b32_e32 v213, 0xffff0000, v30
	v_lshlrev_b32_e32 v214, 16, v31
	v_and_b32_e32 v215, 0xffff0000, v31
	v_lshlrev_b32_e32 v216, 16, v52
	v_and_b32_e32 v217, 0xffff0000, v52
	v_lshlrev_b32_e32 v218, 16, v53
	v_and_b32_e32 v219, 0xffff0000, v53
	v_lshlrev_b32_e32 v220, 16, v54
	v_and_b32_e32 v221, 0xffff0000, v54
	v_lshlrev_b32_e32 v222, 16, v55
	v_and_b32_e32 v223, 0xffff0000, v55
	v_pk_mul_f32 v[154:155], v[208:209], v[216:217]
	v_pk_mul_f32 v[156:157], v[210:211], v[218:219]
	v_pk_mul_f32 v[158:159], v[212:213], v[220:221]
	v_pk_mul_f32 v[160:161], v[214:215], v[222:223]
	v_lshlrev_b32_e32 v208, 16, v32
	v_and_b32_e32 v209, 0xffff0000, v32
	v_lshlrev_b32_e32 v210, 16, v33
	v_and_b32_e32 v211, 0xffff0000, v33
	v_lshlrev_b32_e32 v212, 16, v34
	v_and_b32_e32 v213, 0xffff0000, v34
	v_lshlrev_b32_e32 v214, 16, v35
	v_and_b32_e32 v215, 0xffff0000, v35
	v_lshlrev_b32_e32 v216, 16, v56
	v_and_b32_e32 v217, 0xffff0000, v56
	v_lshlrev_b32_e32 v218, 16, v57
	v_and_b32_e32 v219, 0xffff0000, v57
	v_lshlrev_b32_e32 v220, 16, v58
	v_and_b32_e32 v221, 0xffff0000, v58
	v_lshlrev_b32_e32 v222, 16, v59
	v_and_b32_e32 v223, 0xffff0000, v59
	v_pk_mul_f32 v[162:163], v[208:209], v[216:217]
	v_pk_mul_f32 v[164:165], v[210:211], v[218:219]
	v_pk_mul_f32 v[166:167], v[212:213], v[220:221]
	v_pk_mul_f32 v[168:169], v[214:215], v[222:223]
	v_lshlrev_b32_e32 v208, 16, v36
	v_and_b32_e32 v209, 0xffff0000, v36
	v_lshlrev_b32_e32 v210, 16, v37
	v_and_b32_e32 v211, 0xffff0000, v37
	v_lshlrev_b32_e32 v212, 16, v38
	v_and_b32_e32 v213, 0xffff0000, v38
	v_lshlrev_b32_e32 v214, 16, v39
	v_and_b32_e32 v215, 0xffff0000, v39
	v_lshlrev_b32_e32 v216, 16, v60
	v_and_b32_e32 v217, 0xffff0000, v60
	v_lshlrev_b32_e32 v218, 16, v61
	v_and_b32_e32 v219, 0xffff0000, v61
	v_lshlrev_b32_e32 v220, 16, v62
	v_and_b32_e32 v221, 0xffff0000, v62
	v_lshlrev_b32_e32 v222, 16, v63
	v_and_b32_e32 v223, 0xffff0000, v63
	v_pk_mul_f32 v[170:171], v[208:209], v[216:217]
	v_pk_mul_f32 v[172:173], v[210:211], v[218:219]
	v_pk_mul_f32 v[174:175], v[212:213], v[220:221]
	v_pk_mul_f32 v[176:177], v[214:215], v[222:223]
	v_mul_f32_e32 v128, s98, v128
	v_mul_f32_e32 v129, s98, v129
	v_mul_f32_e32 v130, s98, v130
	v_mul_f32_e32 v131, s98, v131
	v_mul_f32_e32 v132, s98, v132
	v_mul_f32_e32 v133, s98, v133
	v_mul_f32_e32 v134, s98, v134
	v_mul_f32_e32 v135, s98, v135
	v_mul_f32_e32 v170, s99, v170
	v_mul_f32_e32 v171, s99, v171
	v_mul_f32_e32 v172, s99, v172
	v_mul_f32_e32 v173, s99, v173
	v_mul_f32_e32 v174, s99, v174
	v_mul_f32_e32 v175, s99, v175
	v_mul_f32_e32 v176, s99, v176
	v_mul_f32_e32 v177, s99, v177
	v_pk_mul_f32 v[208:209], v[112:113], v[146:147]
	v_pk_mul_f32 v[210:211], v[114:115], v[148:149]
	v_pk_mul_f32 v[212:213], v[116:117], v[150:151]
	v_pk_mul_f32 v[214:215], v[118:119], v[152:153]
	v_pk_fma_f32 v[208:209], v[104:105], v[136:137], v[208:209]
	v_pk_fma_f32 v[210:211], v[106:107], v[138:139], v[210:211]
	v_pk_fma_f32 v[212:213], v[108:109], v[140:141], v[212:213]
	v_pk_fma_f32 v[214:215], v[110:111], v[142:143], v[214:215]
	v_pk_fma_f32 v[208:209], v[96:97], v[128:129], v[208:209]
	v_pk_fma_f32 v[210:211], v[98:99], v[130:131], v[210:211]
	v_pk_fma_f32 v[212:213], v[100:101], v[132:133], v[212:213]
	v_pk_fma_f32 v[214:215], v[102:103], v[134:135], v[214:215]
	v_pk_add_f32 v[208:209], v[120:121], v[208:209]
	v_pk_add_f32 v[210:211], v[122:123], v[210:211]
	v_pk_add_f32 v[212:213], v[124:125], v[212:213]
	v_pk_add_f32 v[214:215], v[126:127], v[214:215]
	v_lshlrev_b32_e32 v216, 16, v64
	v_and_b32_e32 v217, 0xffff0000, v64
	v_lshlrev_b32_e32 v218, 16, v65
	v_and_b32_e32 v219, 0xffff0000, v65
	v_lshlrev_b32_e32 v220, 16, v66
	v_and_b32_e32 v221, 0xffff0000, v66
	v_lshlrev_b32_e32 v222, 16, v67
	v_and_b32_e32 v223, 0xffff0000, v67
	v_pk_mul_f32 v[208:209], v[208:209], v[216:217]
	v_pk_mul_f32 v[210:211], v[210:211], v[218:219]
	v_pk_mul_f32 v[212:213], v[212:213], v[220:221]
	v_pk_mul_f32 v[214:215], v[214:215], v[222:223]
	v_lshlrev_b32_e32 v224, 16, v80
	v_and_b32_e32 v225, 0xffff0000, v80
	v_lshlrev_b32_e32 v226, 16, v81
	v_and_b32_e32 v227, 0xffff0000, v81
	v_lshlrev_b32_e32 v228, 16, v82
	v_and_b32_e32 v229, 0xffff0000, v82
	v_lshlrev_b32_e32 v230, 16, v83
	v_and_b32_e32 v231, 0xffff0000, v83
	v_mul_f32_e32 v232, 0xbfb8aa3b, v224
	v_mul_f32_e32 v233, 0xbfb8aa3b, v225
	v_mul_f32_e32 v234, 0xbfb8aa3b, v226
	v_mul_f32_e32 v235, 0xbfb8aa3b, v227
	v_mul_f32_e32 v236, 0xbfb8aa3b, v228
	v_mul_f32_e32 v237, 0xbfb8aa3b, v229
	v_mul_f32_e32 v238, 0xbfb8aa3b, v230
	v_mul_f32_e32 v239, 0xbfb8aa3b, v231
	v_exp_f32_e32 v232, v232
	v_exp_f32_e32 v233, v233
	v_exp_f32_e32 v234, v234
	v_exp_f32_e32 v235, v235
	v_exp_f32_e32 v236, v236
	v_exp_f32_e32 v237, v237
	v_exp_f32_e32 v238, v238
	v_exp_f32_e32 v239, v239
	v_add_f32_e32 v232, 1.0, v232
	v_add_f32_e32 v233, 1.0, v233
	v_add_f32_e32 v234, 1.0, v234
	v_add_f32_e32 v235, 1.0, v235
	v_add_f32_e32 v236, 1.0, v236
	v_add_f32_e32 v237, 1.0, v237
	v_add_f32_e32 v238, 1.0, v238
	v_add_f32_e32 v239, 1.0, v239
	v_rcp_f32_e32 v232, v232
	v_rcp_f32_e32 v233, v233
	v_rcp_f32_e32 v234, v234
	v_rcp_f32_e32 v235, v235
	v_rcp_f32_e32 v236, v236
	v_rcp_f32_e32 v237, v237
	v_rcp_f32_e32 v238, v238
	v_rcp_f32_e32 v239, v239
	v_pk_mul_f32 v[232:233], v[232:233], v[224:225]
	v_pk_mul_f32 v[234:235], v[234:235], v[226:227]
	v_pk_mul_f32 v[236:237], v[236:237], v[228:229]
	v_pk_mul_f32 v[238:239], v[238:239], v[230:231]
	v_pk_mul_f32 v[208:209], v[208:209], v[232:233]
	v_pk_mul_f32 v[210:211], v[210:211], v[234:235]
	v_pk_mul_f32 v[212:213], v[212:213], v[236:237]
	v_pk_mul_f32 v[214:215], v[214:215], v[238:239]
	v_cvt_pk_bf16_f32 v216, v208, v209
	v_cvt_pk_bf16_f32 v217, v210, v211
	v_cvt_pk_bf16_f32 v218, v212, v213
	v_cvt_pk_bf16_f32 v219, v214, v215
	global_store_dwordx4 v4, v[216:219], s[100:101]
	s_nop 1
	v_pk_mul_f32 v[208:209], v[112:113], v[154:155]
	v_pk_mul_f32 v[210:211], v[114:115], v[156:157]
	v_pk_mul_f32 v[212:213], v[116:117], v[158:159]
	v_pk_mul_f32 v[214:215], v[118:119], v[160:161]
	v_pk_fma_f32 v[208:209], v[104:105], v[146:147], v[208:209]
	v_pk_fma_f32 v[210:211], v[106:107], v[148:149], v[210:211]
	v_pk_fma_f32 v[212:213], v[108:109], v[150:151], v[212:213]
	v_pk_fma_f32 v[214:215], v[110:111], v[152:153], v[214:215]
	v_pk_fma_f32 v[208:209], v[96:97], v[136:137], v[208:209]
	v_pk_fma_f32 v[210:211], v[98:99], v[138:139], v[210:211]
	v_pk_fma_f32 v[212:213], v[100:101], v[140:141], v[212:213]
	v_pk_fma_f32 v[214:215], v[102:103], v[142:143], v[214:215]
	v_pk_add_f32 v[208:209], v[120:121], v[208:209]
	v_pk_add_f32 v[210:211], v[122:123], v[210:211]
	v_pk_add_f32 v[212:213], v[124:125], v[212:213]
	v_pk_add_f32 v[214:215], v[126:127], v[214:215]
	v_lshlrev_b32_e32 v216, 16, v68
	v_and_b32_e32 v217, 0xffff0000, v68
	v_lshlrev_b32_e32 v218, 16, v69
	v_and_b32_e32 v219, 0xffff0000, v69
	v_lshlrev_b32_e32 v220, 16, v70
	v_and_b32_e32 v221, 0xffff0000, v70
	v_lshlrev_b32_e32 v222, 16, v71
	v_and_b32_e32 v223, 0xffff0000, v71
	v_pk_mul_f32 v[208:209], v[208:209], v[216:217]
	v_pk_mul_f32 v[210:211], v[210:211], v[218:219]
	v_pk_mul_f32 v[212:213], v[212:213], v[220:221]
	v_pk_mul_f32 v[214:215], v[214:215], v[222:223]
	v_lshlrev_b32_e32 v224, 16, v84
	v_and_b32_e32 v225, 0xffff0000, v84
	v_lshlrev_b32_e32 v226, 16, v85
	v_and_b32_e32 v227, 0xffff0000, v85
	v_lshlrev_b32_e32 v228, 16, v86
	v_and_b32_e32 v229, 0xffff0000, v86
	v_lshlrev_b32_e32 v230, 16, v87
	v_and_b32_e32 v231, 0xffff0000, v87
	v_mul_f32_e32 v232, 0xbfb8aa3b, v224
	v_mul_f32_e32 v233, 0xbfb8aa3b, v225
	v_mul_f32_e32 v234, 0xbfb8aa3b, v226
	v_mul_f32_e32 v235, 0xbfb8aa3b, v227
	v_mul_f32_e32 v236, 0xbfb8aa3b, v228
	v_mul_f32_e32 v237, 0xbfb8aa3b, v229
	v_mul_f32_e32 v238, 0xbfb8aa3b, v230
	v_mul_f32_e32 v239, 0xbfb8aa3b, v231
	v_exp_f32_e32 v232, v232
	v_exp_f32_e32 v233, v233
	v_exp_f32_e32 v234, v234
	v_exp_f32_e32 v235, v235
	v_exp_f32_e32 v236, v236
	v_exp_f32_e32 v237, v237
	v_exp_f32_e32 v238, v238
	v_exp_f32_e32 v239, v239
	v_add_f32_e32 v232, 1.0, v232
	v_add_f32_e32 v233, 1.0, v233
	v_add_f32_e32 v234, 1.0, v234
	v_add_f32_e32 v235, 1.0, v235
	v_add_f32_e32 v236, 1.0, v236
	v_add_f32_e32 v237, 1.0, v237
	v_add_f32_e32 v238, 1.0, v238
	v_add_f32_e32 v239, 1.0, v239
	v_rcp_f32_e32 v232, v232
	v_rcp_f32_e32 v233, v233
	v_rcp_f32_e32 v234, v234
	v_rcp_f32_e32 v235, v235
	v_rcp_f32_e32 v236, v236
	v_rcp_f32_e32 v237, v237
	v_rcp_f32_e32 v238, v238
	v_rcp_f32_e32 v239, v239
	v_pk_mul_f32 v[232:233], v[232:233], v[224:225]
	v_pk_mul_f32 v[234:235], v[234:235], v[226:227]
	v_pk_mul_f32 v[236:237], v[236:237], v[228:229]
	v_pk_mul_f32 v[238:239], v[238:239], v[230:231]
	v_pk_mul_f32 v[208:209], v[208:209], v[232:233]
	v_pk_mul_f32 v[210:211], v[210:211], v[234:235]
	v_pk_mul_f32 v[212:213], v[212:213], v[236:237]
	v_pk_mul_f32 v[214:215], v[214:215], v[238:239]
	v_cvt_pk_bf16_f32 v216, v208, v209
	v_cvt_pk_bf16_f32 v217, v210, v211
	v_cvt_pk_bf16_f32 v218, v212, v213
	v_cvt_pk_bf16_f32 v219, v214, v215
	global_store_dwordx4 v4, v[216:219], s[100:101] offset:2048
	s_nop 1
	v_pk_mul_f32 v[208:209], v[112:113], v[162:163]
	v_pk_mul_f32 v[210:211], v[114:115], v[164:165]
	v_pk_mul_f32 v[212:213], v[116:117], v[166:167]
	v_pk_mul_f32 v[214:215], v[118:119], v[168:169]
	v_pk_fma_f32 v[208:209], v[104:105], v[154:155], v[208:209]
	v_pk_fma_f32 v[210:211], v[106:107], v[156:157], v[210:211]
	v_pk_fma_f32 v[212:213], v[108:109], v[158:159], v[212:213]
	v_pk_fma_f32 v[214:215], v[110:111], v[160:161], v[214:215]
	v_pk_fma_f32 v[208:209], v[96:97], v[146:147], v[208:209]
	v_pk_fma_f32 v[210:211], v[98:99], v[148:149], v[210:211]
	v_pk_fma_f32 v[212:213], v[100:101], v[150:151], v[212:213]
	v_pk_fma_f32 v[214:215], v[102:103], v[152:153], v[214:215]
	v_pk_add_f32 v[208:209], v[120:121], v[208:209]
	v_pk_add_f32 v[210:211], v[122:123], v[210:211]
	v_pk_add_f32 v[212:213], v[124:125], v[212:213]
	v_pk_add_f32 v[214:215], v[126:127], v[214:215]
	v_lshlrev_b32_e32 v216, 16, v72
	v_and_b32_e32 v217, 0xffff0000, v72
	v_lshlrev_b32_e32 v218, 16, v73
	v_and_b32_e32 v219, 0xffff0000, v73
	v_lshlrev_b32_e32 v220, 16, v74
	v_and_b32_e32 v221, 0xffff0000, v74
	v_lshlrev_b32_e32 v222, 16, v75
	v_and_b32_e32 v223, 0xffff0000, v75
	v_pk_mul_f32 v[208:209], v[208:209], v[216:217]
	v_pk_mul_f32 v[210:211], v[210:211], v[218:219]
	v_pk_mul_f32 v[212:213], v[212:213], v[220:221]
	v_pk_mul_f32 v[214:215], v[214:215], v[222:223]
	v_lshlrev_b32_e32 v224, 16, v88
	v_and_b32_e32 v225, 0xffff0000, v88
	v_lshlrev_b32_e32 v226, 16, v89
	v_and_b32_e32 v227, 0xffff0000, v89
	v_lshlrev_b32_e32 v228, 16, v90
	v_and_b32_e32 v229, 0xffff0000, v90
	v_lshlrev_b32_e32 v230, 16, v91
	v_and_b32_e32 v231, 0xffff0000, v91
	v_mul_f32_e32 v232, 0xbfb8aa3b, v224
	v_mul_f32_e32 v233, 0xbfb8aa3b, v225
	v_mul_f32_e32 v234, 0xbfb8aa3b, v226
	v_mul_f32_e32 v235, 0xbfb8aa3b, v227
	v_mul_f32_e32 v236, 0xbfb8aa3b, v228
	v_mul_f32_e32 v237, 0xbfb8aa3b, v229
	v_mul_f32_e32 v238, 0xbfb8aa3b, v230
	v_mul_f32_e32 v239, 0xbfb8aa3b, v231
	v_exp_f32_e32 v232, v232
	v_exp_f32_e32 v233, v233
	v_exp_f32_e32 v234, v234
	v_exp_f32_e32 v235, v235
	v_exp_f32_e32 v236, v236
	v_exp_f32_e32 v237, v237
	v_exp_f32_e32 v238, v238
	v_exp_f32_e32 v239, v239
	v_add_f32_e32 v232, 1.0, v232
	v_add_f32_e32 v233, 1.0, v233
	v_add_f32_e32 v234, 1.0, v234
	v_add_f32_e32 v235, 1.0, v235
	v_add_f32_e32 v236, 1.0, v236
	v_add_f32_e32 v237, 1.0, v237
	v_add_f32_e32 v238, 1.0, v238
	v_add_f32_e32 v239, 1.0, v239
	v_rcp_f32_e32 v232, v232
	v_rcp_f32_e32 v233, v233
	v_rcp_f32_e32 v234, v234
	v_rcp_f32_e32 v235, v235
	v_rcp_f32_e32 v236, v236
	v_rcp_f32_e32 v237, v237
	v_rcp_f32_e32 v238, v238
	v_rcp_f32_e32 v239, v239
	v_pk_mul_f32 v[232:233], v[232:233], v[224:225]
	v_pk_mul_f32 v[234:235], v[234:235], v[226:227]
	v_pk_mul_f32 v[236:237], v[236:237], v[228:229]
	v_pk_mul_f32 v[238:239], v[238:239], v[230:231]
	v_pk_mul_f32 v[208:209], v[208:209], v[232:233]
	v_pk_mul_f32 v[210:211], v[210:211], v[234:235]
	v_pk_mul_f32 v[212:213], v[212:213], v[236:237]
	v_pk_mul_f32 v[214:215], v[214:215], v[238:239]
	v_cvt_pk_bf16_f32 v216, v208, v209
	v_cvt_pk_bf16_f32 v217, v210, v211
	v_cvt_pk_bf16_f32 v218, v212, v213
	v_cvt_pk_bf16_f32 v219, v214, v215
	global_store_dwordx4 v5, v[216:219], s[100:101]
	s_nop 1
	v_pk_mul_f32 v[208:209], v[112:113], v[170:171]
	v_pk_mul_f32 v[210:211], v[114:115], v[172:173]
	v_pk_mul_f32 v[212:213], v[116:117], v[174:175]
	v_pk_mul_f32 v[214:215], v[118:119], v[176:177]
	v_pk_fma_f32 v[208:209], v[104:105], v[162:163], v[208:209]
	v_pk_fma_f32 v[210:211], v[106:107], v[164:165], v[210:211]
	v_pk_fma_f32 v[212:213], v[108:109], v[166:167], v[212:213]
	v_pk_fma_f32 v[214:215], v[110:111], v[168:169], v[214:215]
	v_pk_fma_f32 v[208:209], v[96:97], v[154:155], v[208:209]
	v_pk_fma_f32 v[210:211], v[98:99], v[156:157], v[210:211]
	v_pk_fma_f32 v[212:213], v[100:101], v[158:159], v[212:213]
	v_pk_fma_f32 v[214:215], v[102:103], v[160:161], v[214:215]
	v_pk_add_f32 v[208:209], v[120:121], v[208:209]
	v_pk_add_f32 v[210:211], v[122:123], v[210:211]
	v_pk_add_f32 v[212:213], v[124:125], v[212:213]
	v_pk_add_f32 v[214:215], v[126:127], v[214:215]
	v_lshlrev_b32_e32 v216, 16, v76
	v_and_b32_e32 v217, 0xffff0000, v76
	v_lshlrev_b32_e32 v218, 16, v77
	v_and_b32_e32 v219, 0xffff0000, v77
	v_lshlrev_b32_e32 v220, 16, v78
	v_and_b32_e32 v221, 0xffff0000, v78
	v_lshlrev_b32_e32 v222, 16, v79
	v_and_b32_e32 v223, 0xffff0000, v79
	v_pk_mul_f32 v[208:209], v[208:209], v[216:217]
	v_pk_mul_f32 v[210:211], v[210:211], v[218:219]
	v_pk_mul_f32 v[212:213], v[212:213], v[220:221]
	v_pk_mul_f32 v[214:215], v[214:215], v[222:223]
	v_lshlrev_b32_e32 v224, 16, v92
	v_and_b32_e32 v225, 0xffff0000, v92
	v_lshlrev_b32_e32 v226, 16, v93
	v_and_b32_e32 v227, 0xffff0000, v93
	v_lshlrev_b32_e32 v228, 16, v94
	v_and_b32_e32 v229, 0xffff0000, v94
	v_lshlrev_b32_e32 v230, 16, v95
	v_and_b32_e32 v231, 0xffff0000, v95
	v_mul_f32_e32 v232, 0xbfb8aa3b, v224
	v_mul_f32_e32 v233, 0xbfb8aa3b, v225
	v_mul_f32_e32 v234, 0xbfb8aa3b, v226
	v_mul_f32_e32 v235, 0xbfb8aa3b, v227
	v_mul_f32_e32 v236, 0xbfb8aa3b, v228
	v_mul_f32_e32 v237, 0xbfb8aa3b, v229
	v_mul_f32_e32 v238, 0xbfb8aa3b, v230
	v_mul_f32_e32 v239, 0xbfb8aa3b, v231
	v_exp_f32_e32 v232, v232
	v_exp_f32_e32 v233, v233
	v_exp_f32_e32 v234, v234
	v_exp_f32_e32 v235, v235
	v_exp_f32_e32 v236, v236
	v_exp_f32_e32 v237, v237
	v_exp_f32_e32 v238, v238
	v_exp_f32_e32 v239, v239
	v_add_f32_e32 v232, 1.0, v232
	v_add_f32_e32 v233, 1.0, v233
	v_add_f32_e32 v234, 1.0, v234
	v_add_f32_e32 v235, 1.0, v235
	v_add_f32_e32 v236, 1.0, v236
	v_add_f32_e32 v237, 1.0, v237
	v_add_f32_e32 v238, 1.0, v238
	v_add_f32_e32 v239, 1.0, v239
	v_rcp_f32_e32 v232, v232
	v_rcp_f32_e32 v233, v233
	v_rcp_f32_e32 v234, v234
	v_rcp_f32_e32 v235, v235
	v_rcp_f32_e32 v236, v236
	v_rcp_f32_e32 v237, v237
	v_rcp_f32_e32 v238, v238
	v_rcp_f32_e32 v239, v239
	v_pk_mul_f32 v[232:233], v[232:233], v[224:225]
	v_pk_mul_f32 v[234:235], v[234:235], v[226:227]
	v_pk_mul_f32 v[236:237], v[236:237], v[228:229]
	v_pk_mul_f32 v[238:239], v[238:239], v[230:231]
	v_pk_mul_f32 v[208:209], v[208:209], v[232:233]
	v_pk_mul_f32 v[210:211], v[210:211], v[234:235]
	v_pk_mul_f32 v[212:213], v[212:213], v[236:237]
	v_pk_mul_f32 v[214:215], v[214:215], v[238:239]
	v_cvt_pk_bf16_f32 v216, v208, v209
	v_cvt_pk_bf16_f32 v217, v210, v211
	v_cvt_pk_bf16_f32 v218, v212, v213
	v_cvt_pk_bf16_f32 v219, v214, v215
	global_store_dwordx4 v5, v[216:219], s[100:101] offset:2048
	s_nop 1

	.amdhsa_kernel _Z14fwd_megakernel6Params
		.amdhsa_group_segment_fixed_size 80916
		.amdhsa_private_segment_fixed_size 0
		.amdhsa_kernarg_size 544
		.amdhsa_user_sgpr_count 2
		.amdhsa_user_sgpr_dispatch_ptr 0
		.amdhsa_user_sgpr_queue_ptr 0
		.amdhsa_user_sgpr_kernarg_segment_ptr 1
		.amdhsa_user_sgpr_dispatch_id 0
		.amdhsa_user_sgpr_kernarg_preload_length 0
		.amdhsa_user_sgpr_kernarg_preload_offset 0
		.amdhsa_user_sgpr_private_segment_size 0
		.amdhsa_uses_dynamic_stack 0
		.amdhsa_enable_private_segment 0
		.amdhsa_system_sgpr_workgroup_id_x 1
		.amdhsa_system_sgpr_workgroup_id_y 0
		.amdhsa_system_sgpr_workgroup_id_z 0
		.amdhsa_system_sgpr_workgroup_info 0
		.amdhsa_system_vgpr_workitem_id 2
		.amdhsa_next_free_vgpr 256
		.amdhsa_next_free_sgpr 102
		.amdhsa_accum_offset 256
		.amdhsa_reserve_vcc 1
		.amdhsa_float_round_mode_32 0
		.amdhsa_float_round_mode_16_64 0
		.amdhsa_float_denorm_mode_32 3
		.amdhsa_float_denorm_mode_16_64 3
		.amdhsa_dx10_clamp 1
		.amdhsa_ieee_mode 1
		.amdhsa_fp16_overflow 0
		.amdhsa_tg_split 0
		.amdhsa_exception_fp_ieee_invalid_op 0
		.amdhsa_exception_fp_denorm_src 0
		.amdhsa_exception_fp_ieee_div_zero 0
		.amdhsa_exception_fp_ieee_overflow 0
		.amdhsa_exception_fp_ieee_underflow 0
		.amdhsa_exception_fp_ieee_inexact 0
		.amdhsa_exception_int_div_zero 0
	.end_amdhsa_kernel

amdhsa.kernels:
  - .agpr_count:     0
    .args:
      - .offset:         0
        .size:           288
        .value_kind:     by_value
      - .offset:         288
        .size:           4
        .value_kind:     hidden_block_count_x
      - .offset:         292
        .size:           4
        .value_kind:     hidden_block_count_y
      - .offset:         296
        .size:           4
        .value_kind:     hidden_block_count_z
      - .offset:         300
        .size:           2
        .value_kind:     hidden_group_size_x
      - .offset:         302
        .size:           2
        .value_kind:     hidden_group_size_y
      - .offset:         304
        .size:           2
        .value_kind:     hidden_group_size_z
      - .offset:         306
        .size:           2
        .value_kind:     hidden_remainder_x
      - .offset:         308
        .size:           2
        .value_kind:     hidden_remainder_y
      - .offset:         310
        .size:           2
        .value_kind:     hidden_remainder_z
      - .offset:         328
        .size:           8
        .value_kind:     hidden_global_offset_x
      - .offset:         336
        .size:           8
        .value_kind:     hidden_global_offset_y
      - .offset:         344
        .size:           8
        .value_kind:     hidden_global_offset_z
      - .offset:         352
        .size:           2
        .value_kind:     hidden_grid_dims
      - .offset:         376
        .size:           8
        .value_kind:     hidden_multigrid_sync_arg
    .group_segment_fixed_size: 80916
    .kernarg_segment_align: 8
    .kernarg_segment_size: 544
    .language:       OpenCL C
    .language_version:
      - 2
      - 0
    .max_flat_workgroup_size: 256
    .name:           _Z14fwd_megakernel6Params
    .private_segment_fixed_size: 0
    .sgpr_count:     108
    .sgpr_spill_count: 239
    .symbol:         _Z14fwd_megakernel6Params.kd
    .uniform_work_group_size: 1
    .uses_dynamic_stack: false
    .vgpr_count:     256
    .vgpr_spill_count: 0
    .wavefront_size: 64
